# window attention: sentinel-extended T5 bias table in LDS read with pipelined ds_read_b32 (replaces 32 exec-masked serial lookups per tile), K/V fragment prefetch, 2-chain row max
# speedup vs baseline: 1.0113x; 1.0113x over previous
; DEV unsigned pk2(float lo, float hi) { return pg8::cvt_pk_bf16(lo, hi); }
; template <int DQK, int DV, int NDP, int MODE, bool PF>
; DEV void attn_unit(unsigned char* lds, const bf16_t* Q, int ldq, const bf16_t* K, int ldk, const bf16_t* VT, int ldvt, bf16_t* O, int ldo,
;                    int kt0, int ntiles, int qpos0, const float* biasg, float sinkl2) {
;     ...
;             float mx = fmaxf(p0[0], p1[0]);
; #pragma unroll
;             for (int r = 1; r < 16; ++r) mx = fmaxf(mx, fmaxf(p0[r], p1[r]));
;             mx = fmaxf(mx, __shfl_xor(mx, 32));
;             const float mnew = fmaxf(mrun, mx), alpha = __builtin_amdgcn_exp2f(mrun - mnew); mrun = mnew;
;             float rsum = 0.f;
; #pragma unroll
;             for (int r = 0; r < 16; ++r) { p0[r] = __builtin_amdgcn_exp2f(p0[r] - mnew); p1[r] = __builtin_amdgcn_exp2f(p1[r] - mnew); rsum += p0[r] + p1[r]; }
;             lrun = lrun * alpha + rsum;
; #pragma unroll
;             for (int i = 0; i < NDB; ++i)
; #pragma unroll
;                 for (int r = 0; r < 16; ++r) o[i][r] *= alpha;
;             bf16x8 pb[4];
; #pragma unroll
;             for (int ks = 0; ks < 4; ++ks) { u32x4 w;
;                 if (ks < 2) { w.x = pk2(p0[8 * ks + 0], p0[8 * ks + 1]); w.y = pk2(p0[8 * ks + 2], p0[8 * ks + 3]); w.z = pk2(p0[8 * ks + 4], p0[8 * ks + 5]); w.w = pk2(p0[8 * ks + 6], p0[8 * ks + 7]); }
;                 else { const int k2 = ks - 2; w.x = pk2(p1[8 * k2 + 0], p1[8 * k2 + 1]); w.y = pk2(p1[8 * k2 + 2], p1[8 * k2 + 3]); w.z = pk2(p1[8 * k2 + 4], p1[8 * k2 + 5]); w.w = pk2(p1[8 * k2 + 6], p1[8 * k2 + 7]); }
;                 pb[ks] = __builtin_bit_cast(bf16x8, w); }
; #pragma unroll
;             for (int db = 0; db < NDB; ++db)
; #pragma unroll
;                 for (int ks = 0; ks < 4; ++ks) {
;                     const bf16x8 vf = *(const bf16x8*)(Vt + (dp * DVW + db * 32 + r32) * VP + ks * 16 + hi * 8);
;                     o[db] = __builtin_amdgcn_mfma_f32_32x32x16_bf16(vf, pb[ks], o[db], 0, 0, 0);
;                 }
.LBB0_1274:
	s_or_b64 exec, exec, s[4:5]
	ds_read_b128 v[188:191], v121 offset:9216
	ds_read_b128 v[192:195], v121 offset:9248
	ds_read_b128 v[196:199], v121 offset:9280
	ds_read_b128 v[200:203], v121 offset:9312
	ds_read_b128 v[204:207], v121 offset:13824
	ds_read_b128 v[208:211], v121 offset:13856
	ds_read_b128 v[212:215], v121 offset:13888
	ds_read_b128 v[216:219], v121 offset:13920
	v_max3_f32 v36, v124, v123, v48
	v_max3_f32 v39, v129, v55, v130
	v_max3_f32 v36, v36, v32, v49
	v_max3_f32 v39, v39, v56, v131
	v_max3_f32 v36, v36, v33, v50
	v_max3_f32 v39, v39, v57, v132
	v_max3_f32 v36, v36, v34, v35
	v_max3_f32 v39, v39, v58, v133
	v_max3_f32 v36, v36, v51, v126
	v_max3_f32 v39, v39, v59, v134
	v_max3_f32 v36, v36, v52, v127
	v_max3_f32 v39, v39, v60, v135
	v_max3_f32 v36, v36, v53, v54
	v_max3_f32 v39, v39, v61, v136
	v_max_f32_e32 v36, v36, v38
	v_max_f32_e32 v39, v39, v62
	v_max_f32_e32 v36, v36, v39
	v_and_b32_e32 v39, 64, v227
	v_xor_b32_e32 v37, 32, v227
	v_add_u32_e32 v39, 64, v39
	v_cmp_lt_i32_e32 vcc, v37, v39
	s_nop 1
	v_cndmask_b32_e32 v37, v227, v37, vcc
	v_lshlrev_b32_e32 v37, 2, v37
	ds_bpermute_b32 v37, v37, v36
	s_waitcnt lgkmcnt(0)
	v_max3_f32 v37, v122, v36, v37
	v_sub_f32_e32 v32, v32, v37
	v_exp_f32_e32 v140, v32
	v_sub_f32_e32 v32, v49, v37
	v_sub_f32_e32 v46, v131, v37
	v_sub_f32_e32 v39, v124, v37
	v_exp_f32_e32 v142, v32
	v_sub_f32_e32 v32, v33, v37
	v_exp_f32_e32 v49, v46
	v_sub_f32_e32 v46, v57, v37
	v_exp_f32_e32 v63, v39
	v_sub_f32_e32 v39, v123, v37
	v_exp_f32_e32 v143, v32
	v_sub_f32_e32 v32, v50, v37
	v_exp_f32_e32 v47, v46
	v_sub_f32_e32 v46, v132, v37
	v_exp_f32_e32 v137, v39
	v_sub_f32_e32 v39, v48, v37
	v_exp_f32_e32 v145, v32
	v_sub_f32_e32 v32, v34, v37
	v_exp_f32_e32 v48, v46
	v_sub_f32_e32 v46, v58, v37
	v_sub_f32_e32 v58, v133, v37
	v_exp_f32_e32 v146, v32
	v_sub_f32_e32 v32, v35, v37
	v_exp_f32_e32 v123, v58
	v_sub_f32_e32 v58, v59, v37
	v_exp_f32_e32 v139, v39
	v_exp_f32_e32 v35, v32
	v_sub_f32_e32 v32, v51, v37
	v_exp_f32_e32 v125, v58
	v_sub_f32_e32 v58, v134, v37
	v_sub_f32_e32 v36, v122, v37
	v_exp_f32_e32 v33, v32
	v_sub_f32_e32 v32, v126, v37
	v_exp_f32_e32 v122, v58
	v_sub_f32_e32 v58, v60, v37
	v_sub_f32_e32 v60, v135, v37
	v_exp_f32_e32 v34, v32
	v_sub_f32_e32 v32, v52, v37
	v_sub_f32_e32 v39, v127, v37
	v_exp_f32_e32 v127, v60
	v_sub_f32_e32 v60, v61, v37
	v_add_f32_e32 v138, v63, v137
	v_exp_f32_e32 v32, v32
	v_sub_f32_e32 v42, v129, v37
	v_exp_f32_e32 v131, v60
	v_sub_f32_e32 v60, v136, v37
	v_add_f32_e32 v141, v139, v140
	v_exp_f32_e32 v41, v39
	v_sub_f32_e32 v39, v53, v37
	v_sub_f32_e32 v40, v54, v37
	v_sub_f32_e32 v38, v38, v37
	v_exp_f32_e32 v45, v42
	v_sub_f32_e32 v42, v55, v37
	v_exp_f32_e32 v126, v60
	v_sub_f32_e32 v60, v62, v37
	v_add_f32_e32 v62, 0, v138
	v_add_f32_e32 v144, v142, v143
	v_exp_f32_e32 v39, v39
	v_exp_f32_e32 v40, v40
	v_exp_f32_e32 v38, v38
	v_exp_f32_e32 v43, v42
	v_sub_f32_e32 v42, v130, v37
	v_add_f32_e32 v62, v141, v62
	v_add_f32_e32 v147, v145, v146
	v_exp_f32_e32 v44, v42
	v_sub_f32_e32 v42, v56, v37
	v_add_f32_e32 v62, v144, v62
	v_pk_add_f32 v[50:51], v[34:35], v[32:33]
	v_exp_f32_e32 v42, v42
	v_add_f32_e32 v62, v147, v62
	v_add_f32_e32 v51, v51, v62
	v_pk_add_f32 v[52:53], v[40:41], v[38:39]
	v_exp_f32_e32 v46, v46
	v_add_f32_e32 v50, v50, v51
	v_add_f32_e32 v50, v53, v50
	v_pk_add_f32 v[54:55], v[44:45], v[42:43]
	v_exp_f32_e32 v124, v58
	v_add_f32_e32 v50, v52, v50
	v_add_f32_e32 v50, v55, v50
	v_pk_add_f32 v[56:57], v[48:49], v[46:47]
	v_exp_f32_e32 v130, v60
	v_add_f32_e32 v50, v54, v50
	v_add_f32_e32 v50, v57, v50
	v_pk_add_f32 v[58:59], v[122:123], v[124:125]
	v_add_f32_e32 v50, v56, v50
	v_add_f32_e32 v50, v59, v50
	v_pk_add_f32 v[60:61], v[126:127], v[130:131]
	v_add_f32_e32 v50, v58, v50
	v_exp_f32_e32 v36, v36
	v_add_f32_e32 v50, v61, v50
	v_add_f32_e32 v50, v60, v50
	v_cvt_pk_bf16_f32 v52, v63, v139
	v_cvt_pk_bf16_f32 v53, v142, v145
	v_cvt_pk_bf16_f32 v54, v35, v34
	v_cvt_pk_bf16_f32 v55, v41, v40
	v_cvt_pk_bf16_f32 v56, v45, v44
	v_cvt_pk_bf16_f32 v57, v49, v48
	v_cvt_pk_bf16_f32 v58, v123, v122
	v_cvt_pk_bf16_f32 v59, v127, v126
	v_cvt_pk_bf16_f32 v60, v137, v140
	v_cvt_pk_bf16_f32 v61, v143, v146
	v_cvt_pk_bf16_f32 v62, v33, v32
	v_cvt_pk_bf16_f32 v63, v39, v38
	v_cvt_pk_bf16_f32 v32, v43, v42
	v_cvt_pk_bf16_f32 v33, v47, v46
	v_cvt_pk_bf16_f32 v34, v125, v124
	v_cvt_pk_bf16_f32 v35, v131, v130
	v_pk_mul_f32 v[16:17], v[16:17], v[36:37] op_sel_hi:[1,0]
	v_pk_mul_f32 v[18:19], v[18:19], v[36:37] op_sel_hi:[1,0]
	v_pk_mul_f32 v[20:21], v[20:21], v[36:37] op_sel_hi:[1,0]
	v_pk_mul_f32 v[22:23], v[22:23], v[36:37] op_sel_hi:[1,0]
	v_pk_mul_f32 v[24:25], v[24:25], v[36:37] op_sel_hi:[1,0]
	v_pk_mul_f32 v[26:27], v[26:27], v[36:37] op_sel_hi:[1,0]
	v_pk_mul_f32 v[28:29], v[28:29], v[36:37] op_sel_hi:[1,0]
	v_pk_mul_f32 v[30:31], v[30:31], v[36:37] op_sel_hi:[1,0]
	v_pk_mul_f32 v[0:1], v[0:1], v[36:37] op_sel_hi:[1,0]
	v_pk_mul_f32 v[2:3], v[2:3], v[36:37] op_sel_hi:[1,0]
	v_mfma_f32_32x32x16_bf16 v[16:31], v[188:191], v[52:55], v[16:31]
	v_mul_f32_e64 v4, v4, v36
	v_mul_f32_e64 v5, v5, v36
	v_mul_f32_e64 v6, v6, v36
	v_mul_f32_e64 v7, v7, v36
	v_pk_mul_f32 v[8:9], v[8:9], v[36:37] op_sel_hi:[1,0]
	v_pk_mul_f32 v[10:11], v[10:11], v[36:37] op_sel_hi:[1,0]
	v_pk_mul_f32 v[12:13], v[12:13], v[36:37] op_sel_hi:[1,0]
	v_pk_mul_f32 v[14:15], v[14:15], v[36:37] op_sel_hi:[1,0]
	v_mfma_f32_32x32x16_bf16 v[16:31], v[192:195], v[56:59], v[16:31]
	v_fmac_f32_e32 v50, v91, v36
	v_mov_b32_e32 v122, v37
	v_mov_b32_e32 v91, v50
	v_mfma_f32_32x32x16_bf16 v[16:31], v[196:199], v[60:63], v[16:31]
	v_mfma_f32_32x32x16_bf16 v[16:31], v[200:203], v[32:35], v[16:31]
	v_mfma_f32_32x32x16_bf16 v[0:15], v[204:207], v[52:55], v[0:15]
	v_mfma_f32_32x32x16_bf16 v[0:15], v[208:211], v[56:59], v[0:15]
	v_mfma_f32_32x32x16_bf16 v[0:15], v[212:215], v[60:63], v[0:15]
	v_mfma_f32_32x32x16_bf16 v[0:15], v[216:219], v[32:35], v[0:15]

; template <int DQK, int DV, int NDP, int MODE, bool PF>
; DEV void attn_unit(unsigned char* lds, const bf16_t* Q, int ldq, const bf16_t* K, int ldk, const bf16_t* VT, int ldvt, bf16_t* O, int ldo,
;                    int kt0, int ntiles, int qpos0, const float* biasg, float sinkl2) {
;     ...
;         __syncthreads();
;         if (!PF) ATT_GLOAD(kt);
;         ATT_LSTORE();
;         if (MODE == 1 && ti == 0) { for (int i = tid; i < 257; i += 512) bt[i] = biasg[i]; }
;         __syncthreads();
;         if (PF && ti + 1 < ntiles) ATT_GLOAD(kt + 64);
;         bool skip = false;
;         if (MODE == 1) { const int qlo = qpos0 + qg * 32; skip = (kt > qlo + 31 + 128) || (kt + 63 < qlo - 128); }
;         if (!skip) {
;             f32x16 p0, p1;
; #pragma unroll
;             for (int r = 0; r < 16; ++r) { p0[r] = 0.f; p1[r] = 0.f; }
; #pragma unroll
;             for (int d0 = 0; d0 < ND0; ++d0) {
;                 const bf16x8 k0 = *(const bf16x8*)(Kt + krow * KP + d0 * 16 + hi * 8), k1 = *(const bf16x8*)(Kt + (32 + krow) * KP + d0 * 16 + hi * 8);
;                 p0 = __builtin_amdgcn_mfma_f32_32x32x16_bf16(k0, qf[d0], p0, 0, 0, 0);
;                 p1 = __builtin_amdgcn_mfma_f32_32x32x16_bf16(k1, qf[d0], p1, 0, 0, 0);
;             }
;             if (MODE == 1) {
; #pragma unroll
;                 for (int r = 0; r < 16; ++r) { const int rel0 = kt + 16 * (r >> 3) + 8 * hi + (r & 7) - qabs, rel1 = rel0 + 32;
;                     const int i0 = min(max(rel0 + 128, 0), 256), i1 = min(max(rel1 + 128, 0), 256);
;                     p0[r] = (rel0 >= -128 && rel0 <= 128) ? p0[r] + bt[i0] : -1e30f; p1[r] = (rel1 >= -128 && rel1 <= 128) ? p1[r] + bt[i1] : -1e30f; }
;             }
;             float mx = fmaxf(p0[0], p1[0]);
; #pragma unroll
;             for (int r = 1; r < 16; ++r) mx = fmaxf(mx, fmaxf(p0[r], p1[r]));
;             mx = fmaxf(mx, __shfl_xor(mx, 32));
;             const float mnew = fmaxf(mrun, mx), alpha = __builtin_amdgcn_exp2f(mrun - mnew); mrun = mnew;
;             float rsum = 0.f;
; #pragma unroll
;             for (int r = 0; r < 16; ++r) { p0[r] = __builtin_amdgcn_exp2f(p0[r] - mnew); p1[r] = __builtin_amdgcn_exp2f(p1[r] - mnew); rsum += p0[r] + p1[r]; }
.LBB0_1279:
	s_or_b64 exec, exec, s[4:5]
	s_cmp_lg_u32 s30, 0
	s_cbranch_scc1 .Lwin_nofill
	v_subrev_u32_e32 v183, 0x60, v224
	v_mov_b32_e32 v184, 0xf149f2ca
	v_cmp_gt_u32_e32 vcc, 0x101, v183
	s_and_saveexec_b64 s[34:35], vcc
	global_load_dword v184, v[96:97], off offset:-384
	s_or_b64 exec, exec, s[34:35]
	v_lshlrev_b32_e32 v183, 2, v224
	s_waitcnt vmcnt(0)
	v_cmp_gt_u32_e32 vcc, 0x1c0, v224
	s_and_saveexec_b64 s[34:35], vcc
	ds_write_b32 v183, v184 offset:20480
	s_or_b64 exec, exec, s[34:35]
.Lwin_nofill:
	s_lshl_b32 s31, s30, 6
	s_add_i32 s6, s31, s66
	s_add_i32 s30, s30, 1
	s_cmp_ge_i32 s30, s27
	s_waitcnt lgkmcnt(0)
	s_barrier
	s_cbranch_scc1 .LBB0_1281
	v_add_u32_e32 v34, s6, v99
	v_ashrrev_i32_e32 v35, 31, v34
	v_lshlrev_b64 v[34:35], 8, v[34:35]
	s_ashr_i32 s7, s6, 31
	v_lshl_add_u64 v[34:35], v[92:93], 0, v[34:35]
	v_lshl_add_u64 v[32:33], s[6:7], 1, v[94:95]
	flat_load_dwordx4 v[80:83], v[34:35]
	flat_load_dwordx4 v[84:87], v[32:33] offset:128
.LBB0_1281:
	s_cmp_gt_i32 s6, s28
	s_cselect_b64 s[4:5], -1, 0
	s_or_b32 s7, s6, 63
	s_cmp_lt_i32 s7, s29
	s_cselect_b64 s[34:35], -1, 0
	s_or_b64 s[4:5], s[4:5], s[34:35]
	s_and_b64 vcc, exec, s[4:5]
	s_cbranch_vccnz .LBB0_1275
	ds_read_b128 v[188:191], v100
	ds_read_b128 v[192:195], v100 offset:4608
	ds_read_b128 v[196:199], v100 offset:32
	ds_read_b128 v[200:203], v100 offset:4640
	ds_read_b128 v[204:207], v100 offset:64
	ds_read_b128 v[208:211], v100 offset:4672
	ds_read_b128 v[212:215], v100 offset:96
	ds_read_b128 v[216:219], v100 offset:4704
	v_add_u32_e32 v125, s6, v101
	v_add_u32_e32 v182, 0xe0, v125
	v_lshlrev_b32_e32 v182, 2, v182
	s_waitcnt lgkmcnt(6)
	v_mfma_f32_32x32x16_bf16 v[48:63], v[188:191], v[64:67], 0
	v_mfma_f32_32x32x16_bf16 v[32:47], v[192:195], v[64:67], 0
	s_waitcnt lgkmcnt(4)
	v_mfma_f32_32x32x16_bf16 v[48:63], v[196:199], v[68:71], v[48:63]
	v_mfma_f32_32x32x16_bf16 v[32:47], v[200:203], v[68:71], v[32:47]
	s_waitcnt lgkmcnt(2)
	v_mfma_f32_32x32x16_bf16 v[48:63], v[204:207], v[72:75], v[48:63]
	v_mfma_f32_32x32x16_bf16 v[32:47], v[208:211], v[72:75], v[32:47]
	s_waitcnt lgkmcnt(0)
	v_mfma_f32_32x32x16_bf16 v[48:63], v[212:215], v[76:79], v[48:63]
	v_mfma_f32_32x32x16_bf16 v[32:47], v[216:219], v[76:79], v[32:47]
	ds_read_b32 v150, v182 offset:20480
	ds_read_b32 v151, v182 offset:20608
	ds_read_b32 v152, v182 offset:20484
	ds_read_b32 v153, v182 offset:20612
	ds_read_b32 v154, v182 offset:20488
	ds_read_b32 v155, v182 offset:20616
	ds_read_b32 v156, v182 offset:20492
	ds_read_b32 v157, v182 offset:20620
	ds_read_b32 v158, v182 offset:20496
	ds_read_b32 v159, v182 offset:20624
	ds_read_b32 v160, v182 offset:20500
	ds_read_b32 v161, v182 offset:20628
	ds_read_b32 v162, v182 offset:20504
	ds_read_b32 v163, v182 offset:20632
	ds_read_b32 v164, v182 offset:20508
	s_waitcnt lgkmcnt(14)
	v_add_f32_e32 v124, v48, v150
	ds_read_b32 v165, v182 offset:20636
	s_waitcnt lgkmcnt(14)
	v_add_f32_e32 v123, v32, v151
	ds_read_b32 v166, v182 offset:20544
	s_waitcnt lgkmcnt(14)
	v_add_f32_e32 v48, v49, v152
	ds_read_b32 v167, v182 offset:20672
	s_waitcnt lgkmcnt(14)
	v_add_f32_e32 v32, v33, v153
	ds_read_b32 v168, v182 offset:20548
	s_waitcnt lgkmcnt(14)
	v_add_f32_e32 v49, v50, v154
	ds_read_b32 v169, v182 offset:20676
	s_waitcnt lgkmcnt(14)
	v_add_f32_e32 v33, v34, v155
	ds_read_b32 v170, v182 offset:20552
	s_waitcnt lgkmcnt(14)
	v_add_f32_e32 v50, v51, v156
	ds_read_b32 v171, v182 offset:20680
	s_waitcnt lgkmcnt(14)
	v_add_f32_e32 v34, v35, v157
	ds_read_b32 v172, v182 offset:20556
	s_waitcnt lgkmcnt(14)
	v_add_f32_e32 v35, v52, v158
	ds_read_b32 v173, v182 offset:20684
	s_waitcnt lgkmcnt(14)
	v_add_f32_e32 v51, v36, v159
	ds_read_b32 v174, v182 offset:20560
	s_waitcnt lgkmcnt(14)
	v_add_f32_e32 v126, v53, v160
	ds_read_b32 v175, v182 offset:20688
	s_waitcnt lgkmcnt(14)
	v_add_f32_e32 v52, v37, v161
	ds_read_b32 v176, v182 offset:20564
	s_waitcnt lgkmcnt(14)
	v_add_f32_e32 v127, v54, v162
	ds_read_b32 v177, v182 offset:20692
	s_waitcnt lgkmcnt(14)
	v_add_f32_e32 v53, v38, v163
	ds_read_b32 v178, v182 offset:20568
	s_waitcnt lgkmcnt(14)
	v_add_f32_e32 v54, v55, v164
	ds_read_b32 v179, v182 offset:20696
	s_waitcnt lgkmcnt(14)
	v_add_f32_e32 v38, v39, v165
	ds_read_b32 v180, v182 offset:20572
	s_waitcnt lgkmcnt(14)
	v_add_f32_e32 v129, v56, v166
	ds_read_b32 v181, v182 offset:20700
	s_waitcnt lgkmcnt(14)
	v_add_f32_e32 v55, v40, v167
	s_waitcnt lgkmcnt(13)
	v_add_f32_e32 v130, v57, v168
	s_waitcnt lgkmcnt(12)
	v_add_f32_e32 v56, v41, v169
	s_waitcnt lgkmcnt(11)
	v_add_f32_e32 v131, v58, v170
	s_waitcnt lgkmcnt(10)
	v_add_f32_e32 v57, v42, v171
	s_waitcnt lgkmcnt(9)
	v_add_f32_e32 v132, v59, v172
	s_waitcnt lgkmcnt(8)
	v_add_f32_e32 v58, v43, v173
	s_waitcnt lgkmcnt(7)
	v_add_f32_e32 v133, v60, v174
	s_waitcnt lgkmcnt(6)
	v_add_f32_e32 v59, v44, v175
	s_waitcnt lgkmcnt(5)
	v_add_f32_e32 v134, v61, v176
	s_waitcnt lgkmcnt(4)
	v_add_f32_e32 v60, v45, v177
	s_waitcnt lgkmcnt(3)
	v_add_f32_e32 v135, v62, v178
	s_waitcnt lgkmcnt(2)
	v_add_f32_e32 v61, v46, v179
	s_waitcnt lgkmcnt(1)
	v_add_f32_e32 v136, v63, v180
	s_waitcnt lgkmcnt(0)
	v_add_f32_e32 v62, v47, v181
	s_branch .LBB0_1274
